# layer-0 RMSNorm+modulate rewritten by hand: all 5 rows of a wave in flight, shift/scale vectors fetched two rows ahead
# speedup vs baseline: 1.0231x; 1.0079x over previous
.LBB0_35:
	s_mov_b64 s[22:23], exec
	v_readlane_b32 s0, v248, 41
	v_lshrrev_b32_e32 v210, 6, v0
	v_readlane_b32 s1, v246, 41
	v_readlane_b32 s36, v248, 50
	v_readfirstlane_b32 s2, v210
	v_readlane_b32 s37, v248, 51
	v_and_b32_e32 v211, 63, v0
	v_lshlrev_b32_e32 v212, 3, v211
	v_lshlrev_b32_e32 v211, 4, v211
	s_add_i32 s34, s0, s2
	s_lshl_b32 s35, s1, 2
	global_load_dwordx4 v[82:85], v211, s[36:37]
	global_load_dwordx4 v[86:89], v211, s[36:37] offset:1024
	global_load_dwordx4 v[90:93], v211, s[36:37] offset:2048
	global_load_dwordx4 v[94:97], v211, s[36:37] offset:3072
.Lnorm0_iter:
	s_cmp_ge_u32 s34, 0x2800
	s_cbranch_scc1 .Lnorm0_done
	s_mov_b32 s40, s34
	s_add_i32 s41, s40, s35
	s_add_i32 s42, s41, s35
	s_add_i32 s43, s42, s35
	s_add_i32 s44, s43, s35
	s_cmp_lt_u32 s41, 0x2800
	s_cselect_b32 s41, s41, s34
	s_cmp_lt_u32 s42, 0x2800
	s_cselect_b32 s42, s42, s34
	s_cmp_lt_u32 s43, 0x2800
	s_cselect_b32 s43, s43, s34
	s_cmp_lt_u32 s44, 0x2800
	s_cselect_b32 s44, s44, s34
	s_sub_u32 s46, s40, 0x2000
	s_lshr_b32 s46, s46, 10
	s_add_i32 s46, s46, 1
	s_cmp_lt_u32 s40, 0x2000
	s_cselect_b32 s46, 0, s46
	s_mul_i32 s46, s46, 0x3000
	s_add_u32 s50, s4, s46
	s_addc_u32 s51, s5, 0
	s_add_u32 s54, s50, 0x1000
	s_addc_u32 s55, s51, 0
	global_load_dwordx4 v[98:101], v211, s[50:51]
	global_load_dwordx4 v[102:105], v211, s[50:51] offset:1024
	global_load_dwordx4 v[106:109], v211, s[50:51] offset:2048
	global_load_dwordx4 v[110:113], v211, s[50:51] offset:3072
	global_load_dwordx4 v[114:117], v211, s[54:55]
	global_load_dwordx4 v[118:121], v211, s[54:55] offset:1024
	global_load_dwordx4 v[122:125], v211, s[54:55] offset:2048
	global_load_dwordx4 v[126:129], v211, s[54:55] offset:3072
	s_sub_u32 s46, s41, 0x2000
	s_lshr_b32 s46, s46, 10
	s_add_i32 s46, s46, 1
	s_cmp_lt_u32 s41, 0x2000
	s_cselect_b32 s46, 0, s46
	s_mul_i32 s46, s46, 0x3000
	s_add_u32 s50, s4, s46
	s_addc_u32 s51, s5, 0
	s_add_u32 s54, s50, 0x1000
	s_addc_u32 s55, s51, 0
	global_load_dwordx4 v[178:181], v211, s[50:51]
	global_load_dwordx4 v[182:185], v211, s[50:51] offset:1024
	global_load_dwordx4 v[186:189], v211, s[50:51] offset:2048
	global_load_dwordx4 v[190:193], v211, s[50:51] offset:3072
	global_load_dwordx4 v[194:197], v211, s[54:55]
	global_load_dwordx4 v[198:201], v211, s[54:55] offset:1024
	global_load_dwordx4 v[202:205], v211, s[54:55] offset:2048
	global_load_dwordx4 v[206:209], v211, s[54:55] offset:3072
	s_cmp_lt_u32 s40, 0x2000
	s_cselect_b32 s48, s76, s78
	s_cselect_b32 s49, s77, s79
	s_cselect_b32 s46, 0, 0x2000
	s_sub_u32 s46, s40, s46
	s_lshl_b32 s46, s46, 12
	s_add_u32 s48, s48, s46
	s_addc_u32 s49, s49, 0
	global_load_dwordx4 v[2:5], v211, s[48:49]
	global_load_dwordx4 v[6:9], v211, s[48:49] offset:1024
	global_load_dwordx4 v[10:13], v211, s[48:49] offset:2048
	global_load_dwordx4 v[14:17], v211, s[48:49] offset:3072
	s_cmp_lt_u32 s41, 0x2000
	s_cselect_b32 s48, s76, s78
	s_cselect_b32 s49, s77, s79
	s_cselect_b32 s46, 0, 0x2000
	s_sub_u32 s46, s41, s46
	s_lshl_b32 s46, s46, 12
	s_add_u32 s48, s48, s46
	s_addc_u32 s49, s49, 0
	global_load_dwordx4 v[18:21], v211, s[48:49]
	global_load_dwordx4 v[22:25], v211, s[48:49] offset:1024
	global_load_dwordx4 v[26:29], v211, s[48:49] offset:2048
	global_load_dwordx4 v[30:33], v211, s[48:49] offset:3072
	s_cmp_lt_u32 s42, 0x2000
	s_cselect_b32 s48, s76, s78
	s_cselect_b32 s49, s77, s79
	s_cselect_b32 s46, 0, 0x2000
	s_sub_u32 s46, s42, s46
	s_lshl_b32 s46, s46, 12
	s_add_u32 s48, s48, s46
	s_addc_u32 s49, s49, 0
	global_load_dwordx4 v[34:37], v211, s[48:49]
	global_load_dwordx4 v[38:41], v211, s[48:49] offset:1024
	global_load_dwordx4 v[42:45], v211, s[48:49] offset:2048
	global_load_dwordx4 v[46:49], v211, s[48:49] offset:3072
	s_cmp_lt_u32 s43, 0x2000
	s_cselect_b32 s48, s76, s78
	s_cselect_b32 s49, s77, s79
	s_cselect_b32 s46, 0, 0x2000
	s_sub_u32 s46, s43, s46
	s_lshl_b32 s46, s46, 12
	s_add_u32 s48, s48, s46
	s_addc_u32 s49, s49, 0
	global_load_dwordx4 v[50:53], v211, s[48:49]
	global_load_dwordx4 v[54:57], v211, s[48:49] offset:1024
	global_load_dwordx4 v[58:61], v211, s[48:49] offset:2048
	global_load_dwordx4 v[62:65], v211, s[48:49] offset:3072
	s_cmp_lt_u32 s44, 0x2000
	s_cselect_b32 s48, s76, s78
	s_cselect_b32 s49, s77, s79
	s_cselect_b32 s46, 0, 0x2000
	s_sub_u32 s46, s44, s46
	s_lshl_b32 s46, s46, 12
	s_add_u32 s48, s48, s46
	s_addc_u32 s49, s49, 0
	global_load_dwordx4 v[66:69], v211, s[48:49]
	global_load_dwordx4 v[70:73], v211, s[48:49] offset:1024
	global_load_dwordx4 v[74:77], v211, s[48:49] offset:2048
	global_load_dwordx4 v[78:81], v211, s[48:49] offset:3072
	s_waitcnt vmcnt(16)
	v_mul_f32_e32 v213, v2, v2
	v_fmac_f32_e32 v213, v3, v3
	v_fmac_f32_e32 v213, v4, v4
	v_fmac_f32_e32 v213, v5, v5
	v_fmac_f32_e32 v213, v6, v6
	v_fmac_f32_e32 v213, v7, v7
	v_fmac_f32_e32 v213, v8, v8
	v_fmac_f32_e32 v213, v9, v9
	v_fmac_f32_e32 v213, v10, v10
	v_fmac_f32_e32 v213, v11, v11
	v_fmac_f32_e32 v213, v12, v12
	v_fmac_f32_e32 v213, v13, v13
	v_fmac_f32_e32 v213, v14, v14
	v_fmac_f32_e32 v213, v15, v15
	v_fmac_f32_e32 v213, v16, v16
	v_fmac_f32_e32 v213, v17, v17
	s_nop 1
	v_add_f32_dpp v213, v213, v213 quad_perm:[1,0,3,2] row_mask:0xf bank_mask:0xf
	s_nop 1
	v_add_f32_dpp v213, v213, v213 quad_perm:[2,3,0,1] row_mask:0xf bank_mask:0xf
	s_nop 1
	v_add_f32_dpp v213, v213, v213 row_ror:4 row_mask:0xf bank_mask:0xf
	s_nop 1
	v_add_f32_dpp v213, v213, v213 row_ror:8 row_mask:0xf bank_mask:0xf
	s_nop 1
	v_add_f32_dpp v213, v213, v213 row_bcast:15 row_mask:0xa bank_mask:0xf
	s_nop 1
	v_add_f32_dpp v213, v213, v213 row_bcast:31 row_mask:0xc bank_mask:0xf
	s_nop 1
	v_readlane_b32 s47, v213, 63
	s_mul_i32 s56, s40, 0x880
	s_add_u32 s56, s8, s56
	s_addc_u32 s57, s9, 0
	v_mov_b32_e32 v214, s47
	v_fmamk_f32 v214, v214, 0x3a800000, v148
	v_rsq_f32_e32 v214, v214
	s_nop 0
	v_pk_mul_f32 v[2:3], v[2:3], v[214:215] op_sel_hi:[1,0]
	v_pk_add_f32 v[114:115], v[114:115], 1.0 op_sel_hi:[1,0]
	v_pk_mul_f32 v[2:3], v[2:3], v[82:83]
	v_pk_fma_f32 v[2:3], v[2:3], v[114:115], v[98:99]
	v_pk_mul_f32 v[4:5], v[4:5], v[214:215] op_sel_hi:[1,0]
	v_pk_add_f32 v[116:117], v[116:117], 1.0 op_sel_hi:[1,0]
	v_pk_mul_f32 v[4:5], v[4:5], v[84:85]
	v_pk_fma_f32 v[4:5], v[4:5], v[116:117], v[100:101]
	v_pk_mul_f32 v[6:7], v[6:7], v[214:215] op_sel_hi:[1,0]
	v_pk_add_f32 v[118:119], v[118:119], 1.0 op_sel_hi:[1,0]
	v_pk_mul_f32 v[6:7], v[6:7], v[86:87]
	v_pk_fma_f32 v[6:7], v[6:7], v[118:119], v[102:103]
	v_pk_mul_f32 v[8:9], v[8:9], v[214:215] op_sel_hi:[1,0]
	v_pk_add_f32 v[120:121], v[120:121], 1.0 op_sel_hi:[1,0]
	v_pk_mul_f32 v[8:9], v[8:9], v[88:89]
	v_pk_fma_f32 v[8:9], v[8:9], v[120:121], v[104:105]
	v_pk_mul_f32 v[10:11], v[10:11], v[214:215] op_sel_hi:[1,0]
	v_pk_add_f32 v[122:123], v[122:123], 1.0 op_sel_hi:[1,0]
	v_pk_mul_f32 v[10:11], v[10:11], v[90:91]
	v_pk_fma_f32 v[10:11], v[10:11], v[122:123], v[106:107]
	v_pk_mul_f32 v[12:13], v[12:13], v[214:215] op_sel_hi:[1,0]
	v_pk_add_f32 v[124:125], v[124:125], 1.0 op_sel_hi:[1,0]
	v_pk_mul_f32 v[12:13], v[12:13], v[92:93]
	v_pk_fma_f32 v[12:13], v[12:13], v[124:125], v[108:109]
	v_pk_mul_f32 v[14:15], v[14:15], v[214:215] op_sel_hi:[1,0]
	v_pk_add_f32 v[126:127], v[126:127], 1.0 op_sel_hi:[1,0]
	v_pk_mul_f32 v[14:15], v[14:15], v[94:95]
	v_pk_fma_f32 v[14:15], v[14:15], v[126:127], v[110:111]
	v_pk_mul_f32 v[16:17], v[16:17], v[214:215] op_sel_hi:[1,0]
	v_pk_add_f32 v[128:129], v[128:129], 1.0 op_sel_hi:[1,0]
	v_pk_mul_f32 v[16:17], v[16:17], v[96:97]
	v_pk_fma_f32 v[16:17], v[16:17], v[128:129], v[112:113]
	v_cvt_pk_bf16_f32 v216, v2, v3
	v_cvt_pk_bf16_f32 v217, v4, v5
	v_cvt_pk_bf16_f32 v218, v6, v7
	v_cvt_pk_bf16_f32 v219, v8, v9
	v_cvt_pk_bf16_f32 v220, v10, v11
	v_cvt_pk_bf16_f32 v221, v12, v13
	v_cvt_pk_bf16_f32 v222, v14, v15
	v_cvt_pk_bf16_f32 v223, v16, v17
	global_store_dwordx2 v212, v[216:217], s[56:57]
	global_store_dwordx2 v212, v[218:219], s[56:57] offset:512
	global_store_dwordx2 v212, v[220:221], s[56:57] offset:1024
	global_store_dwordx2 v212, v[222:223], s[56:57] offset:1536
	s_sub_u32 s46, s42, 0x2000
	s_lshr_b32 s46, s46, 10
	s_add_i32 s46, s46, 1
	s_cmp_lt_u32 s42, 0x2000
	s_cselect_b32 s46, 0, s46
	s_mul_i32 s46, s46, 0x3000
	s_add_u32 s50, s4, s46
	s_addc_u32 s51, s5, 0
	s_add_u32 s54, s50, 0x1000
	s_addc_u32 s55, s51, 0
	global_load_dwordx4 v[98:101], v211, s[50:51]
	global_load_dwordx4 v[102:105], v211, s[50:51] offset:1024
	global_load_dwordx4 v[106:109], v211, s[50:51] offset:2048
	global_load_dwordx4 v[110:113], v211, s[50:51] offset:3072
	global_load_dwordx4 v[114:117], v211, s[54:55]
	global_load_dwordx4 v[118:121], v211, s[54:55] offset:1024
	global_load_dwordx4 v[122:125], v211, s[54:55] offset:2048
	global_load_dwordx4 v[126:129], v211, s[54:55] offset:3072
	s_waitcnt vmcnt(24)
	v_mul_f32_e32 v213, v18, v18
	v_fmac_f32_e32 v213, v19, v19
	v_fmac_f32_e32 v213, v20, v20
	v_fmac_f32_e32 v213, v21, v21
	v_fmac_f32_e32 v213, v22, v22
	v_fmac_f32_e32 v213, v23, v23
	v_fmac_f32_e32 v213, v24, v24
	v_fmac_f32_e32 v213, v25, v25
	v_fmac_f32_e32 v213, v26, v26
	v_fmac_f32_e32 v213, v27, v27
	v_fmac_f32_e32 v213, v28, v28
	v_fmac_f32_e32 v213, v29, v29
	v_fmac_f32_e32 v213, v30, v30
	v_fmac_f32_e32 v213, v31, v31
	v_fmac_f32_e32 v213, v32, v32
	v_fmac_f32_e32 v213, v33, v33
	s_nop 1
	v_add_f32_dpp v213, v213, v213 quad_perm:[1,0,3,2] row_mask:0xf bank_mask:0xf
	s_nop 1
	v_add_f32_dpp v213, v213, v213 quad_perm:[2,3,0,1] row_mask:0xf bank_mask:0xf
	s_nop 1
	v_add_f32_dpp v213, v213, v213 row_ror:4 row_mask:0xf bank_mask:0xf
	s_nop 1
	v_add_f32_dpp v213, v213, v213 row_ror:8 row_mask:0xf bank_mask:0xf
	s_nop 1
	v_add_f32_dpp v213, v213, v213 row_bcast:15 row_mask:0xa bank_mask:0xf
	s_nop 1
	v_add_f32_dpp v213, v213, v213 row_bcast:31 row_mask:0xc bank_mask:0xf
	s_nop 1
	v_readlane_b32 s47, v213, 63
	s_mul_i32 s56, s41, 0x880
	s_add_u32 s56, s8, s56
	s_addc_u32 s57, s9, 0
	v_mov_b32_e32 v214, s47
	v_fmamk_f32 v214, v214, 0x3a800000, v148
	v_rsq_f32_e32 v214, v214
	s_nop 0
	v_pk_mul_f32 v[18:19], v[18:19], v[214:215] op_sel_hi:[1,0]
	v_pk_add_f32 v[194:195], v[194:195], 1.0 op_sel_hi:[1,0]
	v_pk_mul_f32 v[18:19], v[18:19], v[82:83]
	v_pk_fma_f32 v[18:19], v[18:19], v[194:195], v[178:179]
	v_pk_mul_f32 v[20:21], v[20:21], v[214:215] op_sel_hi:[1,0]
	v_pk_add_f32 v[196:197], v[196:197], 1.0 op_sel_hi:[1,0]
	v_pk_mul_f32 v[20:21], v[20:21], v[84:85]
	v_pk_fma_f32 v[20:21], v[20:21], v[196:197], v[180:181]
	v_pk_mul_f32 v[22:23], v[22:23], v[214:215] op_sel_hi:[1,0]
	v_pk_add_f32 v[198:199], v[198:199], 1.0 op_sel_hi:[1,0]
	v_pk_mul_f32 v[22:23], v[22:23], v[86:87]
	v_pk_fma_f32 v[22:23], v[22:23], v[198:199], v[182:183]
	v_pk_mul_f32 v[24:25], v[24:25], v[214:215] op_sel_hi:[1,0]
	v_pk_add_f32 v[200:201], v[200:201], 1.0 op_sel_hi:[1,0]
	v_pk_mul_f32 v[24:25], v[24:25], v[88:89]
	v_pk_fma_f32 v[24:25], v[24:25], v[200:201], v[184:185]
	v_pk_mul_f32 v[26:27], v[26:27], v[214:215] op_sel_hi:[1,0]
	v_pk_add_f32 v[202:203], v[202:203], 1.0 op_sel_hi:[1,0]
	v_pk_mul_f32 v[26:27], v[26:27], v[90:91]
	v_pk_fma_f32 v[26:27], v[26:27], v[202:203], v[186:187]
	v_pk_mul_f32 v[28:29], v[28:29], v[214:215] op_sel_hi:[1,0]
	v_pk_add_f32 v[204:205], v[204:205], 1.0 op_sel_hi:[1,0]
	v_pk_mul_f32 v[28:29], v[28:29], v[92:93]
	v_pk_fma_f32 v[28:29], v[28:29], v[204:205], v[188:189]
	v_pk_mul_f32 v[30:31], v[30:31], v[214:215] op_sel_hi:[1,0]
	v_pk_add_f32 v[206:207], v[206:207], 1.0 op_sel_hi:[1,0]
	v_pk_mul_f32 v[30:31], v[30:31], v[94:95]
	v_pk_fma_f32 v[30:31], v[30:31], v[206:207], v[190:191]
	v_pk_mul_f32 v[32:33], v[32:33], v[214:215] op_sel_hi:[1,0]
	v_pk_add_f32 v[208:209], v[208:209], 1.0 op_sel_hi:[1,0]
	v_pk_mul_f32 v[32:33], v[32:33], v[96:97]
	v_pk_fma_f32 v[32:33], v[32:33], v[208:209], v[192:193]
	v_cvt_pk_bf16_f32 v216, v18, v19
	v_cvt_pk_bf16_f32 v217, v20, v21
	v_cvt_pk_bf16_f32 v218, v22, v23
	v_cvt_pk_bf16_f32 v219, v24, v25
	v_cvt_pk_bf16_f32 v220, v26, v27
	v_cvt_pk_bf16_f32 v221, v28, v29
	v_cvt_pk_bf16_f32 v222, v30, v31
	v_cvt_pk_bf16_f32 v223, v32, v33
	global_store_dwordx2 v212, v[216:217], s[56:57]
	global_store_dwordx2 v212, v[218:219], s[56:57] offset:512
	global_store_dwordx2 v212, v[220:221], s[56:57] offset:1024
	global_store_dwordx2 v212, v[222:223], s[56:57] offset:1536
	s_sub_u32 s46, s43, 0x2000
	s_lshr_b32 s46, s46, 10
	s_add_i32 s46, s46, 1
	s_cmp_lt_u32 s43, 0x2000
	s_cselect_b32 s46, 0, s46
	s_mul_i32 s46, s46, 0x3000
	s_add_u32 s50, s4, s46
	s_addc_u32 s51, s5, 0
	s_add_u32 s54, s50, 0x1000
	s_addc_u32 s55, s51, 0
	global_load_dwordx4 v[178:181], v211, s[50:51]
	global_load_dwordx4 v[182:185], v211, s[50:51] offset:1024
	global_load_dwordx4 v[186:189], v211, s[50:51] offset:2048
	global_load_dwordx4 v[190:193], v211, s[50:51] offset:3072
	global_load_dwordx4 v[194:197], v211, s[54:55]
	global_load_dwordx4 v[198:201], v211, s[54:55] offset:1024
	global_load_dwordx4 v[202:205], v211, s[54:55] offset:2048
	global_load_dwordx4 v[206:209], v211, s[54:55] offset:3072
	s_waitcnt vmcnt(12)
	v_mul_f32_e32 v213, v34, v34
	v_fmac_f32_e32 v213, v35, v35
	v_fmac_f32_e32 v213, v36, v36
	v_fmac_f32_e32 v213, v37, v37
	v_fmac_f32_e32 v213, v38, v38
	v_fmac_f32_e32 v213, v39, v39
	v_fmac_f32_e32 v213, v40, v40
	v_fmac_f32_e32 v213, v41, v41
	v_fmac_f32_e32 v213, v42, v42
	v_fmac_f32_e32 v213, v43, v43
	v_fmac_f32_e32 v213, v44, v44
	v_fmac_f32_e32 v213, v45, v45
	v_fmac_f32_e32 v213, v46, v46
	v_fmac_f32_e32 v213, v47, v47
	v_fmac_f32_e32 v213, v48, v48
	v_fmac_f32_e32 v213, v49, v49
	s_nop 1
	v_add_f32_dpp v213, v213, v213 quad_perm:[1,0,3,2] row_mask:0xf bank_mask:0xf
	s_nop 1
	v_add_f32_dpp v213, v213, v213 quad_perm:[2,3,0,1] row_mask:0xf bank_mask:0xf
	s_nop 1
	v_add_f32_dpp v213, v213, v213 row_ror:4 row_mask:0xf bank_mask:0xf
	s_nop 1
	v_add_f32_dpp v213, v213, v213 row_ror:8 row_mask:0xf bank_mask:0xf
	s_nop 1
	v_add_f32_dpp v213, v213, v213 row_bcast:15 row_mask:0xa bank_mask:0xf
	s_nop 1
	v_add_f32_dpp v213, v213, v213 row_bcast:31 row_mask:0xc bank_mask:0xf
	s_nop 1
	v_readlane_b32 s47, v213, 63
	s_mul_i32 s56, s42, 0x880
	s_add_u32 s56, s8, s56
	s_addc_u32 s57, s9, 0
	v_mov_b32_e32 v214, s47
	v_fmamk_f32 v214, v214, 0x3a800000, v148
	v_rsq_f32_e32 v214, v214
	s_nop 0
	v_pk_mul_f32 v[34:35], v[34:35], v[214:215] op_sel_hi:[1,0]
	v_pk_add_f32 v[114:115], v[114:115], 1.0 op_sel_hi:[1,0]
	v_pk_mul_f32 v[34:35], v[34:35], v[82:83]
	v_pk_fma_f32 v[34:35], v[34:35], v[114:115], v[98:99]
	v_pk_mul_f32 v[36:37], v[36:37], v[214:215] op_sel_hi:[1,0]
	v_pk_add_f32 v[116:117], v[116:117], 1.0 op_sel_hi:[1,0]
	v_pk_mul_f32 v[36:37], v[36:37], v[84:85]
	v_pk_fma_f32 v[36:37], v[36:37], v[116:117], v[100:101]
	v_pk_mul_f32 v[38:39], v[38:39], v[214:215] op_sel_hi:[1,0]
	v_pk_add_f32 v[118:119], v[118:119], 1.0 op_sel_hi:[1,0]
	v_pk_mul_f32 v[38:39], v[38:39], v[86:87]
	v_pk_fma_f32 v[38:39], v[38:39], v[118:119], v[102:103]
	v_pk_mul_f32 v[40:41], v[40:41], v[214:215] op_sel_hi:[1,0]
	v_pk_add_f32 v[120:121], v[120:121], 1.0 op_sel_hi:[1,0]
	v_pk_mul_f32 v[40:41], v[40:41], v[88:89]
	v_pk_fma_f32 v[40:41], v[40:41], v[120:121], v[104:105]
	v_pk_mul_f32 v[42:43], v[42:43], v[214:215] op_sel_hi:[1,0]
	v_pk_add_f32 v[122:123], v[122:123], 1.0 op_sel_hi:[1,0]
	v_pk_mul_f32 v[42:43], v[42:43], v[90:91]
	v_pk_fma_f32 v[42:43], v[42:43], v[122:123], v[106:107]
	v_pk_mul_f32 v[44:45], v[44:45], v[214:215] op_sel_hi:[1,0]
	v_pk_add_f32 v[124:125], v[124:125], 1.0 op_sel_hi:[1,0]
	v_pk_mul_f32 v[44:45], v[44:45], v[92:93]
	v_pk_fma_f32 v[44:45], v[44:45], v[124:125], v[108:109]
	v_pk_mul_f32 v[46:47], v[46:47], v[214:215] op_sel_hi:[1,0]
	v_pk_add_f32 v[126:127], v[126:127], 1.0 op_sel_hi:[1,0]
	v_pk_mul_f32 v[46:47], v[46:47], v[94:95]
	v_pk_fma_f32 v[46:47], v[46:47], v[126:127], v[110:111]
	v_pk_mul_f32 v[48:49], v[48:49], v[214:215] op_sel_hi:[1,0]
	v_pk_add_f32 v[128:129], v[128:129], 1.0 op_sel_hi:[1,0]
	v_pk_mul_f32 v[48:49], v[48:49], v[96:97]
	v_pk_fma_f32 v[48:49], v[48:49], v[128:129], v[112:113]
	v_cvt_pk_bf16_f32 v216, v34, v35
	v_cvt_pk_bf16_f32 v217, v36, v37
	v_cvt_pk_bf16_f32 v218, v38, v39
	v_cvt_pk_bf16_f32 v219, v40, v41
	v_cvt_pk_bf16_f32 v220, v42, v43
	v_cvt_pk_bf16_f32 v221, v44, v45
	v_cvt_pk_bf16_f32 v222, v46, v47
	v_cvt_pk_bf16_f32 v223, v48, v49
	global_store_dwordx2 v212, v[216:217], s[56:57]
	global_store_dwordx2 v212, v[218:219], s[56:57] offset:512
	global_store_dwordx2 v212, v[220:221], s[56:57] offset:1024
	global_store_dwordx2 v212, v[222:223], s[56:57] offset:1536
	s_sub_u32 s46, s44, 0x2000
	s_lshr_b32 s46, s46, 10
	s_add_i32 s46, s46, 1
	s_cmp_lt_u32 s44, 0x2000
	s_cselect_b32 s46, 0, s46
	s_mul_i32 s46, s46, 0x3000
	s_add_u32 s50, s4, s46
	s_addc_u32 s51, s5, 0
	s_add_u32 s54, s50, 0x1000
	s_addc_u32 s55, s51, 0
	global_load_dwordx4 v[98:101], v211, s[50:51]
	global_load_dwordx4 v[102:105], v211, s[50:51] offset:1024
	global_load_dwordx4 v[106:109], v211, s[50:51] offset:2048
	global_load_dwordx4 v[110:113], v211, s[50:51] offset:3072
	global_load_dwordx4 v[114:117], v211, s[54:55]
	global_load_dwordx4 v[118:121], v211, s[54:55] offset:1024
	global_load_dwordx4 v[122:125], v211, s[54:55] offset:2048
	global_load_dwordx4 v[126:129], v211, s[54:55] offset:3072
	s_waitcnt vmcnt(12)
	v_mul_f32_e32 v213, v50, v50
	v_fmac_f32_e32 v213, v51, v51
	v_fmac_f32_e32 v213, v52, v52
	v_fmac_f32_e32 v213, v53, v53
	v_fmac_f32_e32 v213, v54, v54
	v_fmac_f32_e32 v213, v55, v55
	v_fmac_f32_e32 v213, v56, v56
	v_fmac_f32_e32 v213, v57, v57
	v_fmac_f32_e32 v213, v58, v58
	v_fmac_f32_e32 v213, v59, v59
	v_fmac_f32_e32 v213, v60, v60
	v_fmac_f32_e32 v213, v61, v61
	v_fmac_f32_e32 v213, v62, v62
	v_fmac_f32_e32 v213, v63, v63
	v_fmac_f32_e32 v213, v64, v64
	v_fmac_f32_e32 v213, v65, v65
	s_nop 1
	v_add_f32_dpp v213, v213, v213 quad_perm:[1,0,3,2] row_mask:0xf bank_mask:0xf
	s_nop 1
	v_add_f32_dpp v213, v213, v213 quad_perm:[2,3,0,1] row_mask:0xf bank_mask:0xf
	s_nop 1
	v_add_f32_dpp v213, v213, v213 row_ror:4 row_mask:0xf bank_mask:0xf
	s_nop 1
	v_add_f32_dpp v213, v213, v213 row_ror:8 row_mask:0xf bank_mask:0xf
	s_nop 1
	v_add_f32_dpp v213, v213, v213 row_bcast:15 row_mask:0xa bank_mask:0xf
	s_nop 1
	v_add_f32_dpp v213, v213, v213 row_bcast:31 row_mask:0xc bank_mask:0xf
	s_nop 1
	v_readlane_b32 s47, v213, 63
	s_mul_i32 s56, s43, 0x880
	s_add_u32 s56, s8, s56
	s_addc_u32 s57, s9, 0
	v_mov_b32_e32 v214, s47
	v_fmamk_f32 v214, v214, 0x3a800000, v148
	v_rsq_f32_e32 v214, v214
	s_nop 0
	v_pk_mul_f32 v[50:51], v[50:51], v[214:215] op_sel_hi:[1,0]
	v_pk_add_f32 v[194:195], v[194:195], 1.0 op_sel_hi:[1,0]
	v_pk_mul_f32 v[50:51], v[50:51], v[82:83]
	v_pk_fma_f32 v[50:51], v[50:51], v[194:195], v[178:179]
	v_pk_mul_f32 v[52:53], v[52:53], v[214:215] op_sel_hi:[1,0]
	v_pk_add_f32 v[196:197], v[196:197], 1.0 op_sel_hi:[1,0]
	v_pk_mul_f32 v[52:53], v[52:53], v[84:85]
	v_pk_fma_f32 v[52:53], v[52:53], v[196:197], v[180:181]
	v_pk_mul_f32 v[54:55], v[54:55], v[214:215] op_sel_hi:[1,0]
	v_pk_add_f32 v[198:199], v[198:199], 1.0 op_sel_hi:[1,0]
	v_pk_mul_f32 v[54:55], v[54:55], v[86:87]
	v_pk_fma_f32 v[54:55], v[54:55], v[198:199], v[182:183]
	v_pk_mul_f32 v[56:57], v[56:57], v[214:215] op_sel_hi:[1,0]
	v_pk_add_f32 v[200:201], v[200:201], 1.0 op_sel_hi:[1,0]
	v_pk_mul_f32 v[56:57], v[56:57], v[88:89]
	v_pk_fma_f32 v[56:57], v[56:57], v[200:201], v[184:185]
	v_pk_mul_f32 v[58:59], v[58:59], v[214:215] op_sel_hi:[1,0]
	v_pk_add_f32 v[202:203], v[202:203], 1.0 op_sel_hi:[1,0]
	v_pk_mul_f32 v[58:59], v[58:59], v[90:91]
	v_pk_fma_f32 v[58:59], v[58:59], v[202:203], v[186:187]
	v_pk_mul_f32 v[60:61], v[60:61], v[214:215] op_sel_hi:[1,0]
	v_pk_add_f32 v[204:205], v[204:205], 1.0 op_sel_hi:[1,0]
	v_pk_mul_f32 v[60:61], v[60:61], v[92:93]
	v_pk_fma_f32 v[60:61], v[60:61], v[204:205], v[188:189]
	v_pk_mul_f32 v[62:63], v[62:63], v[214:215] op_sel_hi:[1,0]
	v_pk_add_f32 v[206:207], v[206:207], 1.0 op_sel_hi:[1,0]
	v_pk_mul_f32 v[62:63], v[62:63], v[94:95]
	v_pk_fma_f32 v[62:63], v[62:63], v[206:207], v[190:191]
	v_pk_mul_f32 v[64:65], v[64:65], v[214:215] op_sel_hi:[1,0]
	v_pk_add_f32 v[208:209], v[208:209], 1.0 op_sel_hi:[1,0]
	v_pk_mul_f32 v[64:65], v[64:65], v[96:97]
	v_pk_fma_f32 v[64:65], v[64:65], v[208:209], v[192:193]
	v_cvt_pk_bf16_f32 v216, v50, v51
	v_cvt_pk_bf16_f32 v217, v52, v53
	v_cvt_pk_bf16_f32 v218, v54, v55
	v_cvt_pk_bf16_f32 v219, v56, v57
	v_cvt_pk_bf16_f32 v220, v58, v59
	v_cvt_pk_bf16_f32 v221, v60, v61
	v_cvt_pk_bf16_f32 v222, v62, v63
	v_cvt_pk_bf16_f32 v223, v64, v65
	global_store_dwordx2 v212, v[216:217], s[56:57]
	global_store_dwordx2 v212, v[218:219], s[56:57] offset:512
	global_store_dwordx2 v212, v[220:221], s[56:57] offset:1024
	global_store_dwordx2 v212, v[222:223], s[56:57] offset:1536
	s_waitcnt vmcnt(4)
	v_mul_f32_e32 v213, v66, v66
	v_fmac_f32_e32 v213, v67, v67
	v_fmac_f32_e32 v213, v68, v68
	v_fmac_f32_e32 v213, v69, v69
	v_fmac_f32_e32 v213, v70, v70
	v_fmac_f32_e32 v213, v71, v71
	v_fmac_f32_e32 v213, v72, v72
	v_fmac_f32_e32 v213, v73, v73
	v_fmac_f32_e32 v213, v74, v74
	v_fmac_f32_e32 v213, v75, v75
	v_fmac_f32_e32 v213, v76, v76
	v_fmac_f32_e32 v213, v77, v77
	v_fmac_f32_e32 v213, v78, v78
	v_fmac_f32_e32 v213, v79, v79
	v_fmac_f32_e32 v213, v80, v80
	v_fmac_f32_e32 v213, v81, v81
	s_nop 1
	v_add_f32_dpp v213, v213, v213 quad_perm:[1,0,3,2] row_mask:0xf bank_mask:0xf
	s_nop 1
	v_add_f32_dpp v213, v213, v213 quad_perm:[2,3,0,1] row_mask:0xf bank_mask:0xf
	s_nop 1
	v_add_f32_dpp v213, v213, v213 row_ror:4 row_mask:0xf bank_mask:0xf
	s_nop 1
	v_add_f32_dpp v213, v213, v213 row_ror:8 row_mask:0xf bank_mask:0xf
	s_nop 1
	v_add_f32_dpp v213, v213, v213 row_bcast:15 row_mask:0xa bank_mask:0xf
	s_nop 1
	v_add_f32_dpp v213, v213, v213 row_bcast:31 row_mask:0xc bank_mask:0xf
	s_nop 1
	v_readlane_b32 s47, v213, 63
	s_mul_i32 s56, s44, 0x880
	s_add_u32 s56, s8, s56
	s_addc_u32 s57, s9, 0
	v_mov_b32_e32 v214, s47
	v_fmamk_f32 v214, v214, 0x3a800000, v148
	v_rsq_f32_e32 v214, v214
	s_nop 0
	v_pk_mul_f32 v[66:67], v[66:67], v[214:215] op_sel_hi:[1,0]
	v_pk_add_f32 v[114:115], v[114:115], 1.0 op_sel_hi:[1,0]
	v_pk_mul_f32 v[66:67], v[66:67], v[82:83]
	v_pk_fma_f32 v[66:67], v[66:67], v[114:115], v[98:99]
	v_pk_mul_f32 v[68:69], v[68:69], v[214:215] op_sel_hi:[1,0]
	v_pk_add_f32 v[116:117], v[116:117], 1.0 op_sel_hi:[1,0]
	v_pk_mul_f32 v[68:69], v[68:69], v[84:85]
	v_pk_fma_f32 v[68:69], v[68:69], v[116:117], v[100:101]
	v_pk_mul_f32 v[70:71], v[70:71], v[214:215] op_sel_hi:[1,0]
	v_pk_add_f32 v[118:119], v[118:119], 1.0 op_sel_hi:[1,0]
	v_pk_mul_f32 v[70:71], v[70:71], v[86:87]
	v_pk_fma_f32 v[70:71], v[70:71], v[118:119], v[102:103]
	v_pk_mul_f32 v[72:73], v[72:73], v[214:215] op_sel_hi:[1,0]
	v_pk_add_f32 v[120:121], v[120:121], 1.0 op_sel_hi:[1,0]
	v_pk_mul_f32 v[72:73], v[72:73], v[88:89]
	v_pk_fma_f32 v[72:73], v[72:73], v[120:121], v[104:105]
	v_pk_mul_f32 v[74:75], v[74:75], v[214:215] op_sel_hi:[1,0]
	v_pk_add_f32 v[122:123], v[122:123], 1.0 op_sel_hi:[1,0]
	v_pk_mul_f32 v[74:75], v[74:75], v[90:91]
	v_pk_fma_f32 v[74:75], v[74:75], v[122:123], v[106:107]
	v_pk_mul_f32 v[76:77], v[76:77], v[214:215] op_sel_hi:[1,0]
	v_pk_add_f32 v[124:125], v[124:125], 1.0 op_sel_hi:[1,0]
	v_pk_mul_f32 v[76:77], v[76:77], v[92:93]
	v_pk_fma_f32 v[76:77], v[76:77], v[124:125], v[108:109]
	v_pk_mul_f32 v[78:79], v[78:79], v[214:215] op_sel_hi:[1,0]
	v_pk_add_f32 v[126:127], v[126:127], 1.0 op_sel_hi:[1,0]
	v_pk_mul_f32 v[78:79], v[78:79], v[94:95]
	v_pk_fma_f32 v[78:79], v[78:79], v[126:127], v[110:111]
	v_pk_mul_f32 v[80:81], v[80:81], v[214:215] op_sel_hi:[1,0]
	v_pk_add_f32 v[128:129], v[128:129], 1.0 op_sel_hi:[1,0]
	v_pk_mul_f32 v[80:81], v[80:81], v[96:97]
	v_pk_fma_f32 v[80:81], v[80:81], v[128:129], v[112:113]
	v_cvt_pk_bf16_f32 v216, v66, v67
	v_cvt_pk_bf16_f32 v217, v68, v69
	v_cvt_pk_bf16_f32 v218, v70, v71
	v_cvt_pk_bf16_f32 v219, v72, v73
	v_cvt_pk_bf16_f32 v220, v74, v75
	v_cvt_pk_bf16_f32 v221, v76, v77
	v_cvt_pk_bf16_f32 v222, v78, v79
	v_cvt_pk_bf16_f32 v223, v80, v81
	global_store_dwordx2 v212, v[216:217], s[56:57]
	global_store_dwordx2 v212, v[218:219], s[56:57] offset:512
	global_store_dwordx2 v212, v[220:221], s[56:57] offset:1024
	global_store_dwordx2 v212, v[222:223], s[56:57] offset:1536
	s_mul_i32 s46, s35, 5
	s_add_i32 s34, s34, s46
	s_branch .Lnorm0_iter
.Lnorm0_done:
.LBB0_38:
	s_or_b64 exec, exec, s[22:23]
	s_mov_b64 s[0:1], 0
